# in-proj tail tile split into two half tiles (128x128) run by two WGs, depth-2 prefetch loop, plus A-loop code placement restored to original 32B residue with unreachable padding
# speedup vs baseline: 1.0231x; 1.0090x over previous
; template <bool VT>
; DI void gemm_mainloop(f32x4 (&acc)[8][4], const char* abase, const char* bbase, unsigned toff, u16* sA, u16* sB, int loff, int wm, int wn, int fr, int fq) {
;   const __amdgpu_buffer_rsrc_t ra_rs = __builtin_amdgcn_make_buffer_rsrc((void*)abase, (short)0, 256 * 2048, 0x00020000);
;   const __amdgpu_buffer_rsrc_t rb_rs = __builtin_amdgcn_make_buffer_rsrc((void*)bbase, (short)0, 128 * 2048, 0x00020000);
;   u32x4 ra[8], rb[4];
; #pragma unroll
;   for (int i = 0; i < 8; ++i) ra[i] = __builtin_amdgcn_raw_buffer_load_b128(ra_rs, (int)toff, i * 65536, 0);
; #pragma unroll
;   for (int i = 0; i < 4; ++i) rb[i] = __builtin_amdgcn_raw_buffer_load_b128(rb_rs, (int)toff, i * 65536, 0);
; template <int EPI>
; DI void gemm_tile(const Params& p, int layer, int mt, int nt, u16* sm, int wv) {
;     ...
; #pragma unroll
;   for (int i = 0; i < 8; ++i)
; #pragma unroll
;     for (int j = 0; j < 4; ++j)
; #pragma unroll
;       for (int e = 0; e < 4; ++e) acc[i][j][e] = 0.f;
.Lh0_pro:
	s_mov_b32 s87, s67
	s_mov_b32 s42, 0x40000
	s_mov_b32 s43, 0x50000
	s_mov_b32 s46, 0x0
	s_mov_b32 s47, 0x10000
	s_mov_b32 s70, 0x20000
	s_mov_b32 s71, 0x30000
	buffer_load_dwordx4 v[146:149], v0, s[64:67], s42 offen
	buffer_load_dwordx4 v[150:153], v0, s[64:67], s43 offen
	buffer_load_dwordx4 v[130:133], v0, s[64:67], s46 offen
	buffer_load_dwordx4 v[138:141], v0, s[64:67], s47 offen
	buffer_load_dwordx4 v[162:165], v0, s[84:87], s46 offen
	buffer_load_dwordx4 v[170:173], v0, s[84:87], s47 offen
	buffer_load_dwordx4 v[166:169], v0, s[84:87], s70 offen
	buffer_load_dwordx4 v[174:177], v0, s[84:87], s71 offen
	v_mov_b32_e32 v10, 0
	v_add_u32_e32 v184, v181, v182
	v_add_u32_e32 v185, v181, v183
	v_mov_b32_e32 v11, v10
	v_mov_b32_e32 v12, v10
	v_mov_b32_e32 v13, v10
	v_mov_b32_e32 v2, v10
	v_mov_b32_e32 v3, v10
	v_mov_b32_e32 v4, v10
	v_mov_b32_e32 v5, v10
	v_mov_b32_e32 v6, v10
	v_mov_b32_e32 v7, v10
	v_mov_b32_e32 v8, v10
	v_mov_b32_e32 v9, v10
	v_mov_b32_e32 v14, v10
	v_mov_b32_e32 v15, v10
	v_mov_b32_e32 v16, v10
	v_mov_b32_e32 v17, v10
	v_mov_b32_e32 v18, v10
	v_mov_b32_e32 v19, v10
	v_mov_b32_e32 v20, v10
	v_mov_b32_e32 v21, v10
	v_mov_b32_e32 v22, v10
	v_mov_b32_e32 v23, v10
	v_mov_b32_e32 v24, v10
	v_mov_b32_e32 v25, v10
	v_mov_b32_e32 v26, v10
	v_mov_b32_e32 v27, v10
	v_mov_b32_e32 v28, v10
	v_mov_b32_e32 v29, v10
	v_mov_b32_e32 v30, v10
	v_mov_b32_e32 v31, v10
	v_mov_b32_e32 v32, v10
	v_mov_b32_e32 v33, v10
	v_mov_b32_e32 v34, v10
	v_mov_b32_e32 v35, v10
	v_mov_b32_e32 v36, v10
	v_mov_b32_e32 v37, v10
	v_mov_b32_e32 v38, v10
	v_mov_b32_e32 v39, v10
	v_mov_b32_e32 v40, v10
	v_mov_b32_e32 v41, v10
	v_mov_b32_e32 v42, v10
	v_mov_b32_e32 v43, v10
	v_mov_b32_e32 v44, v10
	v_mov_b32_e32 v45, v10
	v_mov_b32_e32 v46, v10
	v_mov_b32_e32 v47, v10
	v_mov_b32_e32 v48, v10
	v_mov_b32_e32 v49, v10
	v_mov_b32_e32 v50, v10
	v_mov_b32_e32 v51, v10
	v_mov_b32_e32 v52, v10
	v_mov_b32_e32 v53, v10
	v_mov_b32_e32 v54, v10
	v_mov_b32_e32 v55, v10
	v_mov_b32_e32 v56, v10
	v_mov_b32_e32 v57, v10
	v_mov_b32_e32 v58, v10
	v_mov_b32_e32 v59, v10
	v_mov_b32_e32 v60, v10
	v_mov_b32_e32 v61, v10
	v_mov_b32_e32 v62, v10
	v_mov_b32_e32 v63, v10
	v_mov_b32_e32 v64, v10
	v_mov_b32_e32 v65, v10
	v_mov_b32_e32 v66, v10
	v_mov_b32_e32 v67, v10
	v_mov_b32_e32 v68, v10
	v_mov_b32_e32 v69, v10
	v_mov_b32_e32 v70, v10
	v_mov_b32_e32 v71, v10
	v_mov_b32_e32 v72, v10
	v_mov_b32_e32 v73, v10
	v_mov_b32_e32 v74, v10
	v_mov_b32_e32 v75, v10
	v_mov_b32_e32 v76, v10
	v_mov_b32_e32 v77, v10
	v_mov_b32_e32 v78, v10
	v_mov_b32_e32 v79, v10
	v_mov_b32_e32 v80, v10
	v_mov_b32_e32 v81, v10
	v_mov_b32_e32 v82, v10
	v_mov_b32_e32 v83, v10
	v_mov_b32_e32 v84, v10
	v_mov_b32_e32 v85, v10
	v_mov_b32_e32 v86, v10
	v_mov_b32_e32 v87, v10
	v_mov_b32_e32 v88, v10
	v_mov_b32_e32 v89, v10
	v_mov_b32_e32 v90, v10
	v_mov_b32_e32 v91, v10
	v_mov_b32_e32 v92, v10
	v_mov_b32_e32 v93, v10
	v_mov_b32_e32 v94, v10
	v_mov_b32_e32 v95, v10
	v_mov_b32_e32 v96, v10
	v_mov_b32_e32 v97, v10
	v_mov_b32_e32 v98, v10
	v_mov_b32_e32 v99, v10
	v_mov_b32_e32 v100, v10
	v_mov_b32_e32 v101, v10
	v_mov_b32_e32 v102, v10
	v_mov_b32_e32 v103, v10
	v_mov_b32_e32 v104, v10
	v_mov_b32_e32 v105, v10
	v_mov_b32_e32 v106, v10
	v_mov_b32_e32 v107, v10
	v_mov_b32_e32 v108, v10
	v_mov_b32_e32 v109, v10
	v_mov_b32_e32 v110, v10
	v_mov_b32_e32 v111, v10
	v_mov_b32_e32 v112, v10
	v_mov_b32_e32 v113, v10
	v_mov_b32_e32 v114, v10
	v_mov_b32_e32 v115, v10
	v_mov_b32_e32 v116, v10
	v_mov_b32_e32 v117, v10
	v_mov_b32_e32 v118, v10
	v_mov_b32_e32 v119, v10
	v_mov_b32_e32 v120, v10
	v_mov_b32_e32 v121, v10
	v_mov_b32_e32 v122, v10
	v_mov_b32_e32 v123, v10
	v_mov_b32_e32 v124, v10
	v_mov_b32_e32 v125, v10
	v_mov_b32_e32 v126, v10
	v_mov_b32_e32 v127, v10
	v_mov_b32_e32 v128, v10
	v_mov_b32_e32 v129, v10
	s_waitcnt vmcnt(8)
	buffer_load_dwordx4 v[134:137], v0, s[64:67], s42 offen offset:128
	buffer_load_dwordx4 v[142:145], v0, s[64:67], s43 offen offset:128
	buffer_load_dwordx4 v[154:157], v0, s[64:67], s46 offen offset:128
	buffer_load_dwordx4 v[158:161], v0, s[64:67], s47 offen offset:128
	buffer_load_dwordx4 v[2:5], v0, s[84:87], s46 offen offset:128
	buffer_load_dwordx4 v[6:9], v0, s[84:87], s47 offen offset:128
	buffer_load_dwordx4 v[10:13], v0, s[84:87], s70 offen offset:128
	buffer_load_dwordx4 v[14:17], v0, s[84:87], s71 offen offset:128
	s_mov_b32 s32, 7
; DI f32x4 mfma16(bf16x8 a, bf16x8 b, f32x4 c) { return __builtin_amdgcn_mfma_f32_16x16x32_bf16(a, b, c, 0, 0, 0); }
; template <bool VT>
; DI void gemm_kslab(f32x4 (&acc)[8][4], const u16* sA, const u16* sB, int wm, int wn, int fr, int fq) {
; #pragma unroll
;   for (int ks = 0; ks < 2; ++ks) {
;     bf16x8 tb[4], ta[8];
; #pragma unroll
;     for (int j = 0; j < 4; ++j) tb[j] = ldsv(sB + (wn * 64 + 16 * j + fr) * GSTR + ks * 32 + 8 * fq);
; #pragma unroll
;     for (int i = 0; i < 8; ++i) ta[i] = ldsv(sA + (wm * 128 + 16 * i + fr) * GSTR + ks * 32 + 8 * fq);
; #pragma unroll
;     for (int i = 0; i < 8; ++i)
; #pragma unroll
;       for (int j = 0; j < 4; ++j)
;         acc[i][j] = VT ? mfma16(ta[i], tb[j], acc[i][j]) : mfma16(tb[j], ta[i], acc[i][j]);
;   }
; template <bool VT>
; DI void gemm_mainloop(f32x4 (&acc)[8][4], const char* abase, const char* bbase, unsigned toff, u16* sA, u16* sB, int loff, int wm, int wn, int fr, int fq) {
;     ...
; #pragma unroll 1
;   for (int kt = 0; kt < 16; ++kt) {
;     __syncthreads();
; #pragma unroll
;     for (int i = 0; i < 8; ++i) *(u32x4*)(sA + loff + i * 32 * GSTR) = ra[i];
; #pragma unroll
;     for (int i = 0; i < 4; ++i) *(u32x4*)(sB + loff + i * 32 * GSTR) = rb[i];
;     __syncthreads();
;     if (kt + 1 < 16) {
;       const int ko = (kt + 1) * 128;
; #pragma unroll
;       for (int i = 0; i < 8; ++i) ra[i] = __builtin_amdgcn_raw_buffer_load_b128(ra_rs, (int)toff, i * 65536 + ko, 0);
; #pragma unroll
;       for (int i = 0; i < 4; ++i) rb[i] = __builtin_amdgcn_raw_buffer_load_b128(rb_rs, (int)toff, i * 65536 + ko, 0);
;     }
;     __builtin_amdgcn_s_setprio(1);
;     gemm_kslab<VT>(acc, sA, sB, wm, wn, fr, fq);
;     __builtin_amdgcn_s_setprio(0);
.Lh0_loop:
	s_barrier
	s_waitcnt vmcnt(15)
	ds_write_b128 v180, v[146:149] offset:20480
	s_waitcnt vmcnt(14)
	ds_write_b128 v180, v[150:153] offset:25600
	s_waitcnt vmcnt(13)
	ds_write_b128 v180, v[130:133]
	s_waitcnt vmcnt(12)
	ds_write_b128 v180, v[138:141] offset:5120
	s_waitcnt vmcnt(11)
	ds_write_b128 v180, v[162:165] offset:40960
	s_waitcnt vmcnt(10)
	ds_write_b128 v180, v[170:173] offset:46080
	s_waitcnt vmcnt(9)
	ds_write_b128 v180, v[166:169] offset:51200
	s_waitcnt vmcnt(8)
	ds_write_b128 v180, v[174:177] offset:56320
	s_waitcnt lgkmcnt(0)
	s_barrier
	s_addk_i32 s42, 0x100
	s_addk_i32 s43, 0x100
	s_addk_i32 s46, 0x100
	s_addk_i32 s47, 0x100
	s_addk_i32 s70, 0x100
	s_addk_i32 s71, 0x100
	buffer_load_dwordx4 v[146:149], v0, s[64:67], s42 offen
	buffer_load_dwordx4 v[150:153], v0, s[64:67], s43 offen
	buffer_load_dwordx4 v[130:133], v0, s[64:67], s46 offen
	buffer_load_dwordx4 v[138:141], v0, s[64:67], s47 offen
	buffer_load_dwordx4 v[162:165], v0, s[84:87], s46 offen
	buffer_load_dwordx4 v[170:173], v0, s[84:87], s47 offen
	buffer_load_dwordx4 v[166:169], v0, s[84:87], s70 offen
	buffer_load_dwordx4 v[174:177], v0, s[84:87], s71 offen
	s_setprio 1
	ds_read_b128 v[202:205], v184 offset:40960
	ds_read_b128 v[206:209], v184 offset:43520
	ds_read_b128 v[214:217], v184 offset:46080
	ds_read_b128 v[218:221], v184 offset:48640
	ds_read_b128 v[210:213], v185
	ds_read_b128 v[222:225], v185 offset:2560
	s_waitcnt lgkmcnt(1)
	v_mfma_f32_16x16x32_bf16 v[126:129], v[202:205], v[210:213], v[126:129]
	v_mfma_f32_16x16x32_bf16 v[122:125], v[206:209], v[210:213], v[122:125]
	v_mfma_f32_16x16x32_bf16 v[118:121], v[214:217], v[210:213], v[118:121]
	v_mfma_f32_16x16x32_bf16 v[114:117], v[218:221], v[210:213], v[114:117]
	ds_read_b128 v[210:213], v185 offset:5120
	s_waitcnt lgkmcnt(1)
	v_mfma_f32_16x16x32_bf16 v[110:113], v[202:205], v[222:225], v[110:113]
	v_mfma_f32_16x16x32_bf16 v[106:109], v[206:209], v[222:225], v[106:109]
	v_mfma_f32_16x16x32_bf16 v[102:105], v[214:217], v[222:225], v[102:105]
	v_mfma_f32_16x16x32_bf16 v[98:101], v[218:221], v[222:225], v[98:101]
	ds_read_b128 v[222:225], v185 offset:7680
	ds_read_b128 v[226:229], v184 offset:41024
	ds_read_b128 v[230:233], v184 offset:43584
	ds_read_b128 v[234:237], v184 offset:46144
	ds_read_b128 v[238:241], v184 offset:48704
	ds_read_b128 v[242:245], v185 offset:64
	ds_read_b128 v[246:249], v185 offset:2624
	s_waitcnt lgkmcnt(7)
	v_mfma_f32_16x16x32_bf16 v[94:97], v[202:205], v[210:213], v[94:97]
	v_mfma_f32_16x16x32_bf16 v[90:93], v[206:209], v[210:213], v[90:93]
	v_mfma_f32_16x16x32_bf16 v[86:89], v[214:217], v[210:213], v[86:89]
	v_mfma_f32_16x16x32_bf16 v[82:85], v[218:221], v[210:213], v[82:85]
	s_waitcnt lgkmcnt(6)
	v_mfma_f32_16x16x32_bf16 v[78:81], v[202:205], v[222:225], v[78:81]
	v_mfma_f32_16x16x32_bf16 v[74:77], v[206:209], v[222:225], v[74:77]
	v_mfma_f32_16x16x32_bf16 v[70:73], v[214:217], v[222:225], v[70:73]
	v_mfma_f32_16x16x32_bf16 v[66:69], v[218:221], v[222:225], v[66:69]
	s_waitcnt lgkmcnt(1)
	v_mfma_f32_16x16x32_bf16 v[126:129], v[226:229], v[242:245], v[126:129]
	v_mfma_f32_16x16x32_bf16 v[122:125], v[230:233], v[242:245], v[122:125]
	v_mfma_f32_16x16x32_bf16 v[118:121], v[234:237], v[242:245], v[118:121]
	v_mfma_f32_16x16x32_bf16 v[114:117], v[238:241], v[242:245], v[114:117]
	ds_read_b128 v[202:205], v185 offset:5184
	s_waitcnt lgkmcnt(1)
	v_mfma_f32_16x16x32_bf16 v[110:113], v[226:229], v[246:249], v[110:113]
	v_mfma_f32_16x16x32_bf16 v[106:109], v[230:233], v[246:249], v[106:109]
	v_mfma_f32_16x16x32_bf16 v[102:105], v[234:237], v[246:249], v[102:105]
	v_mfma_f32_16x16x32_bf16 v[98:101], v[238:241], v[246:249], v[98:101]
	ds_read_b128 v[206:209], v185 offset:7744
	s_waitcnt lgkmcnt(1)
	v_mfma_f32_16x16x32_bf16 v[94:97], v[226:229], v[202:205], v[94:97]
	v_mfma_f32_16x16x32_bf16 v[90:93], v[230:233], v[202:205], v[90:93]
	v_mfma_f32_16x16x32_bf16 v[86:89], v[234:237], v[202:205], v[86:89]
	v_mfma_f32_16x16x32_bf16 v[82:85], v[238:241], v[202:205], v[82:85]
	s_waitcnt lgkmcnt(0)
	v_mfma_f32_16x16x32_bf16 v[78:81], v[226:229], v[206:209], v[78:81]
	v_mfma_f32_16x16x32_bf16 v[74:77], v[230:233], v[206:209], v[74:77]
	v_mfma_f32_16x16x32_bf16 v[70:73], v[234:237], v[206:209], v[70:73]
	v_mfma_f32_16x16x32_bf16 v[66:69], v[238:241], v[206:209], v[66:69]
	s_setprio 0
	s_barrier
	s_waitcnt vmcnt(15)
	ds_write_b128 v180, v[134:137] offset:20480
	s_waitcnt vmcnt(14)
	ds_write_b128 v180, v[142:145] offset:25600
	s_waitcnt vmcnt(13)
	ds_write_b128 v180, v[154:157]
	s_waitcnt vmcnt(12)
	ds_write_b128 v180, v[158:161] offset:5120
	s_waitcnt vmcnt(11)
	ds_write_b128 v180, v[2:5] offset:40960
	s_waitcnt vmcnt(10)
	ds_write_b128 v180, v[6:9] offset:46080
	s_waitcnt vmcnt(9)
	ds_write_b128 v180, v[10:13] offset:51200
	s_waitcnt vmcnt(8)
	ds_write_b128 v180, v[14:17] offset:56320
	s_waitcnt lgkmcnt(0)
	s_barrier
; DI f32x4 mfma16(bf16x8 a, bf16x8 b, f32x4 c) { return __builtin_amdgcn_mfma_f32_16x16x32_bf16(a, b, c, 0, 0, 0); }
; template <bool VT>
; DI void gemm_kslab(f32x4 (&acc)[8][4], const u16* sA, const u16* sB, int wm, int wn, int fr, int fq) {
; #pragma unroll
;   for (int ks = 0; ks < 2; ++ks) {
;     bf16x8 tb[4], ta[8];
; #pragma unroll
;     for (int j = 0; j < 4; ++j) tb[j] = ldsv(sB + (wn * 64 + 16 * j + fr) * GSTR + ks * 32 + 8 * fq);
; #pragma unroll
;     for (int i = 0; i < 8; ++i) ta[i] = ldsv(sA + (wm * 128 + 16 * i + fr) * GSTR + ks * 32 + 8 * fq);
; #pragma unroll
;     for (int i = 0; i < 8; ++i)
; #pragma unroll
;       for (int j = 0; j < 4; ++j)
;         acc[i][j] = VT ? mfma16(ta[i], tb[j], acc[i][j]) : mfma16(tb[j], ta[i], acc[i][j]);
;   }
; template <bool VT>
; DI void gemm_mainloop(f32x4 (&acc)[8][4], const char* abase, const char* bbase, unsigned toff, u16* sA, u16* sB, int loff, int wm, int wn, int fr, int fq) {
;     ...
; #pragma unroll 1
;   for (int kt = 0; kt < 16; ++kt) {
;     __syncthreads();
; #pragma unroll
;     for (int i = 0; i < 8; ++i) *(u32x4*)(sA + loff + i * 32 * GSTR) = ra[i];
; #pragma unroll
;     for (int i = 0; i < 4; ++i) *(u32x4*)(sB + loff + i * 32 * GSTR) = rb[i];
;     __syncthreads();
;     if (kt + 1 < 16) {
;       const int ko = (kt + 1) * 128;
; #pragma unroll
;       for (int i = 0; i < 8; ++i) ra[i] = __builtin_amdgcn_raw_buffer_load_b128(ra_rs, (int)toff, i * 65536 + ko, 0);
; #pragma unroll
;       for (int i = 0; i < 4; ++i) rb[i] = __builtin_amdgcn_raw_buffer_load_b128(rb_rs, (int)toff, i * 65536 + ko, 0);
;     }
;     __builtin_amdgcn_s_setprio(1);
;     gemm_kslab<VT>(acc, sA, sB, wm, wn, fr, fq);
;     __builtin_amdgcn_s_setprio(0);
	buffer_load_dwordx4 v[134:137], v0, s[64:67], s42 offen offset:128
	buffer_load_dwordx4 v[142:145], v0, s[64:67], s43 offen offset:128
	buffer_load_dwordx4 v[154:157], v0, s[64:67], s46 offen offset:128
	buffer_load_dwordx4 v[158:161], v0, s[64:67], s47 offen offset:128
	buffer_load_dwordx4 v[2:5], v0, s[84:87], s46 offen offset:128
	buffer_load_dwordx4 v[6:9], v0, s[84:87], s47 offen offset:128
	buffer_load_dwordx4 v[10:13], v0, s[84:87], s70 offen offset:128
	buffer_load_dwordx4 v[14:17], v0, s[84:87], s71 offen offset:128
	s_setprio 1
	ds_read_b128 v[202:205], v184 offset:40960
	ds_read_b128 v[206:209], v184 offset:43520
	ds_read_b128 v[214:217], v184 offset:46080
	ds_read_b128 v[218:221], v184 offset:48640
	ds_read_b128 v[210:213], v185
	ds_read_b128 v[222:225], v185 offset:2560
	s_waitcnt lgkmcnt(1)
	v_mfma_f32_16x16x32_bf16 v[126:129], v[202:205], v[210:213], v[126:129]
	v_mfma_f32_16x16x32_bf16 v[122:125], v[206:209], v[210:213], v[122:125]
	v_mfma_f32_16x16x32_bf16 v[118:121], v[214:217], v[210:213], v[118:121]
	v_mfma_f32_16x16x32_bf16 v[114:117], v[218:221], v[210:213], v[114:117]
	ds_read_b128 v[210:213], v185 offset:5120
	s_waitcnt lgkmcnt(1)
	v_mfma_f32_16x16x32_bf16 v[110:113], v[202:205], v[222:225], v[110:113]
	v_mfma_f32_16x16x32_bf16 v[106:109], v[206:209], v[222:225], v[106:109]
	v_mfma_f32_16x16x32_bf16 v[102:105], v[214:217], v[222:225], v[102:105]
	v_mfma_f32_16x16x32_bf16 v[98:101], v[218:221], v[222:225], v[98:101]
	ds_read_b128 v[222:225], v185 offset:7680
	ds_read_b128 v[226:229], v184 offset:41024
	ds_read_b128 v[230:233], v184 offset:43584
	ds_read_b128 v[234:237], v184 offset:46144
	ds_read_b128 v[238:241], v184 offset:48704
	ds_read_b128 v[242:245], v185 offset:64
	ds_read_b128 v[246:249], v185 offset:2624
	s_waitcnt lgkmcnt(7)
	v_mfma_f32_16x16x32_bf16 v[94:97], v[202:205], v[210:213], v[94:97]
	v_mfma_f32_16x16x32_bf16 v[90:93], v[206:209], v[210:213], v[90:93]
	v_mfma_f32_16x16x32_bf16 v[86:89], v[214:217], v[210:213], v[86:89]
	v_mfma_f32_16x16x32_bf16 v[82:85], v[218:221], v[210:213], v[82:85]
	s_waitcnt lgkmcnt(6)
	v_mfma_f32_16x16x32_bf16 v[78:81], v[202:205], v[222:225], v[78:81]
	v_mfma_f32_16x16x32_bf16 v[74:77], v[206:209], v[222:225], v[74:77]
	v_mfma_f32_16x16x32_bf16 v[70:73], v[214:217], v[222:225], v[70:73]
	v_mfma_f32_16x16x32_bf16 v[66:69], v[218:221], v[222:225], v[66:69]
	s_waitcnt lgkmcnt(1)
	v_mfma_f32_16x16x32_bf16 v[126:129], v[226:229], v[242:245], v[126:129]
	v_mfma_f32_16x16x32_bf16 v[122:125], v[230:233], v[242:245], v[122:125]
	v_mfma_f32_16x16x32_bf16 v[118:121], v[234:237], v[242:245], v[118:121]
	v_mfma_f32_16x16x32_bf16 v[114:117], v[238:241], v[242:245], v[114:117]
	ds_read_b128 v[202:205], v185 offset:5184
	s_waitcnt lgkmcnt(1)
	v_mfma_f32_16x16x32_bf16 v[110:113], v[226:229], v[246:249], v[110:113]
	v_mfma_f32_16x16x32_bf16 v[106:109], v[230:233], v[246:249], v[106:109]
	v_mfma_f32_16x16x32_bf16 v[102:105], v[234:237], v[246:249], v[102:105]
	v_mfma_f32_16x16x32_bf16 v[98:101], v[238:241], v[246:249], v[98:101]
	ds_read_b128 v[206:209], v185 offset:7744
	s_waitcnt lgkmcnt(1)
	v_mfma_f32_16x16x32_bf16 v[94:97], v[226:229], v[202:205], v[94:97]
	v_mfma_f32_16x16x32_bf16 v[90:93], v[230:233], v[202:205], v[90:93]
	v_mfma_f32_16x16x32_bf16 v[86:89], v[234:237], v[202:205], v[86:89]
	v_mfma_f32_16x16x32_bf16 v[82:85], v[238:241], v[202:205], v[82:85]
	s_waitcnt lgkmcnt(0)
	v_mfma_f32_16x16x32_bf16 v[78:81], v[226:229], v[206:209], v[78:81]
	v_mfma_f32_16x16x32_bf16 v[74:77], v[230:233], v[206:209], v[74:77]
	v_mfma_f32_16x16x32_bf16 v[70:73], v[234:237], v[206:209], v[70:73]
	v_mfma_f32_16x16x32_bf16 v[66:69], v[238:241], v[206:209], v[66:69]
	s_setprio 0
	s_sub_i32 s32, s32, 1
	s_cmp_lg_u32 s32, 0
	s_cbranch_scc1 .Lh0_loop
	s_barrier
	s_waitcnt vmcnt(15)
	ds_write_b128 v180, v[146:149] offset:20480
	s_waitcnt vmcnt(14)
	ds_write_b128 v180, v[150:153] offset:25600
	s_waitcnt vmcnt(13)
	ds_write_b128 v180, v[130:133]
	s_waitcnt vmcnt(12)
	ds_write_b128 v180, v[138:141] offset:5120
	s_waitcnt vmcnt(11)
	ds_write_b128 v180, v[162:165] offset:40960
	s_waitcnt vmcnt(10)
	ds_write_b128 v180, v[170:173] offset:46080
	s_waitcnt vmcnt(9)
	ds_write_b128 v180, v[166:169] offset:51200
	s_waitcnt vmcnt(8)
	ds_write_b128 v180, v[174:177] offset:56320
	s_waitcnt lgkmcnt(0)
	s_barrier
; DI f32x4 mfma16(bf16x8 a, bf16x8 b, f32x4 c) { return __builtin_amdgcn_mfma_f32_16x16x32_bf16(a, b, c, 0, 0, 0); }
; template <bool VT>
; DI void gemm_kslab(f32x4 (&acc)[8][4], const u16* sA, const u16* sB, int wm, int wn, int fr, int fq) {
; #pragma unroll
;   for (int ks = 0; ks < 2; ++ks) {
;     bf16x8 tb[4], ta[8];
; #pragma unroll
;     for (int j = 0; j < 4; ++j) tb[j] = ldsv(sB + (wn * 64 + 16 * j + fr) * GSTR + ks * 32 + 8 * fq);
; #pragma unroll
;     for (int i = 0; i < 8; ++i) ta[i] = ldsv(sA + (wm * 128 + 16 * i + fr) * GSTR + ks * 32 + 8 * fq);
; #pragma unroll
;     for (int i = 0; i < 8; ++i)
; #pragma unroll
;       for (int j = 0; j < 4; ++j)
;         acc[i][j] = VT ? mfma16(ta[i], tb[j], acc[i][j]) : mfma16(tb[j], ta[i], acc[i][j]);
;   }
; template <bool VT>
; DI void gemm_mainloop(f32x4 (&acc)[8][4], const char* abase, const char* bbase, unsigned toff, u16* sA, u16* sB, int loff, int wm, int wn, int fr, int fq) {
;     ...
; #pragma unroll 1
;   for (int kt = 0; kt < 16; ++kt) {
;     __syncthreads();
; #pragma unroll
;     for (int i = 0; i < 8; ++i) *(u32x4*)(sA + loff + i * 32 * GSTR) = ra[i];
; #pragma unroll
;     for (int i = 0; i < 4; ++i) *(u32x4*)(sB + loff + i * 32 * GSTR) = rb[i];
;     __syncthreads();
;     if (kt + 1 < 16) {
;       const int ko = (kt + 1) * 128;
; #pragma unroll
;       for (int i = 0; i < 8; ++i) ra[i] = __builtin_amdgcn_raw_buffer_load_b128(ra_rs, (int)toff, i * 65536 + ko, 0);
; #pragma unroll
;       for (int i = 0; i < 4; ++i) rb[i] = __builtin_amdgcn_raw_buffer_load_b128(rb_rs, (int)toff, i * 65536 + ko, 0);
;     }
;     __builtin_amdgcn_s_setprio(1);
;     gemm_kslab<VT>(acc, sA, sB, wm, wn, fr, fq);
;     __builtin_amdgcn_s_setprio(0);
	s_setprio 1
	ds_read_b128 v[202:205], v184 offset:40960
	ds_read_b128 v[206:209], v184 offset:43520
	ds_read_b128 v[214:217], v184 offset:46080
	ds_read_b128 v[218:221], v184 offset:48640
	ds_read_b128 v[210:213], v185
	ds_read_b128 v[222:225], v185 offset:2560
	s_waitcnt lgkmcnt(1)
	v_mfma_f32_16x16x32_bf16 v[126:129], v[202:205], v[210:213], v[126:129]
	v_mfma_f32_16x16x32_bf16 v[122:125], v[206:209], v[210:213], v[122:125]
	v_mfma_f32_16x16x32_bf16 v[118:121], v[214:217], v[210:213], v[118:121]
	v_mfma_f32_16x16x32_bf16 v[114:117], v[218:221], v[210:213], v[114:117]
	ds_read_b128 v[210:213], v185 offset:5120
	s_waitcnt lgkmcnt(1)
	v_mfma_f32_16x16x32_bf16 v[110:113], v[202:205], v[222:225], v[110:113]
	v_mfma_f32_16x16x32_bf16 v[106:109], v[206:209], v[222:225], v[106:109]
	v_mfma_f32_16x16x32_bf16 v[102:105], v[214:217], v[222:225], v[102:105]
	v_mfma_f32_16x16x32_bf16 v[98:101], v[218:221], v[222:225], v[98:101]
	ds_read_b128 v[222:225], v185 offset:7680
	ds_read_b128 v[226:229], v184 offset:41024
	ds_read_b128 v[230:233], v184 offset:43584
	ds_read_b128 v[234:237], v184 offset:46144
	ds_read_b128 v[238:241], v184 offset:48704
	ds_read_b128 v[242:245], v185 offset:64
	ds_read_b128 v[246:249], v185 offset:2624
	s_waitcnt lgkmcnt(7)
	v_mfma_f32_16x16x32_bf16 v[94:97], v[202:205], v[210:213], v[94:97]
	v_mfma_f32_16x16x32_bf16 v[90:93], v[206:209], v[210:213], v[90:93]
	v_mfma_f32_16x16x32_bf16 v[86:89], v[214:217], v[210:213], v[86:89]
	v_mfma_f32_16x16x32_bf16 v[82:85], v[218:221], v[210:213], v[82:85]
	s_waitcnt lgkmcnt(6)
	v_mfma_f32_16x16x32_bf16 v[78:81], v[202:205], v[222:225], v[78:81]
	v_mfma_f32_16x16x32_bf16 v[74:77], v[206:209], v[222:225], v[74:77]
	v_mfma_f32_16x16x32_bf16 v[70:73], v[214:217], v[222:225], v[70:73]
	v_mfma_f32_16x16x32_bf16 v[66:69], v[218:221], v[222:225], v[66:69]
	s_waitcnt lgkmcnt(1)
	v_mfma_f32_16x16x32_bf16 v[126:129], v[226:229], v[242:245], v[126:129]
	v_mfma_f32_16x16x32_bf16 v[122:125], v[230:233], v[242:245], v[122:125]
	v_mfma_f32_16x16x32_bf16 v[118:121], v[234:237], v[242:245], v[118:121]
	v_mfma_f32_16x16x32_bf16 v[114:117], v[238:241], v[242:245], v[114:117]
	ds_read_b128 v[202:205], v185 offset:5184
	s_waitcnt lgkmcnt(1)
	v_mfma_f32_16x16x32_bf16 v[110:113], v[226:229], v[246:249], v[110:113]
	v_mfma_f32_16x16x32_bf16 v[106:109], v[230:233], v[246:249], v[106:109]
	v_mfma_f32_16x16x32_bf16 v[102:105], v[234:237], v[246:249], v[102:105]
	v_mfma_f32_16x16x32_bf16 v[98:101], v[238:241], v[246:249], v[98:101]
	ds_read_b128 v[206:209], v185 offset:7744
	s_waitcnt lgkmcnt(1)
	v_mfma_f32_16x16x32_bf16 v[94:97], v[226:229], v[202:205], v[94:97]
	v_mfma_f32_16x16x32_bf16 v[90:93], v[230:233], v[202:205], v[90:93]
	v_mfma_f32_16x16x32_bf16 v[86:89], v[234:237], v[202:205], v[86:89]
	v_mfma_f32_16x16x32_bf16 v[82:85], v[238:241], v[202:205], v[82:85]
	s_waitcnt lgkmcnt(0)
	v_mfma_f32_16x16x32_bf16 v[78:81], v[226:229], v[206:209], v[78:81]
	v_mfma_f32_16x16x32_bf16 v[74:77], v[230:233], v[206:209], v[74:77]
	v_mfma_f32_16x16x32_bf16 v[70:73], v[234:237], v[206:209], v[70:73]
	v_mfma_f32_16x16x32_bf16 v[66:69], v[238:241], v[206:209], v[66:69]
	s_setprio 0
	s_barrier
	s_waitcnt vmcnt(7)
	ds_write_b128 v180, v[134:137] offset:20480
	s_waitcnt vmcnt(6)
	ds_write_b128 v180, v[142:145] offset:25600
	s_waitcnt vmcnt(5)
	ds_write_b128 v180, v[154:157]
	s_waitcnt vmcnt(4)
	ds_write_b128 v180, v[158:161] offset:5120
	s_waitcnt vmcnt(3)
	ds_write_b128 v180, v[2:5] offset:40960
	s_waitcnt vmcnt(2)
	ds_write_b128 v180, v[6:9] offset:46080
	s_waitcnt vmcnt(1)
	ds_write_b128 v180, v[10:13] offset:51200
	s_waitcnt vmcnt(0)
	ds_write_b128 v180, v[14:17] offset:56320
	s_waitcnt lgkmcnt(0)
	s_barrier
	s_setprio 1
	ds_read_b128 v[202:205], v184 offset:40960
	ds_read_b128 v[206:209], v184 offset:43520
	ds_read_b128 v[214:217], v184 offset:46080
	ds_read_b128 v[218:221], v184 offset:48640
	ds_read_b128 v[210:213], v185
	ds_read_b128 v[222:225], v185 offset:2560
	s_waitcnt lgkmcnt(1)
	v_mfma_f32_16x16x32_bf16 v[126:129], v[202:205], v[210:213], v[126:129]
	v_mfma_f32_16x16x32_bf16 v[122:125], v[206:209], v[210:213], v[122:125]
	v_mfma_f32_16x16x32_bf16 v[118:121], v[214:217], v[210:213], v[118:121]
	v_mfma_f32_16x16x32_bf16 v[114:117], v[218:221], v[210:213], v[114:117]
	ds_read_b128 v[210:213], v185 offset:5120
	s_waitcnt lgkmcnt(1)
	v_mfma_f32_16x16x32_bf16 v[110:113], v[202:205], v[222:225], v[110:113]
	v_mfma_f32_16x16x32_bf16 v[106:109], v[206:209], v[222:225], v[106:109]
	v_mfma_f32_16x16x32_bf16 v[102:105], v[214:217], v[222:225], v[102:105]
	v_mfma_f32_16x16x32_bf16 v[98:101], v[218:221], v[222:225], v[98:101]
	ds_read_b128 v[222:225], v185 offset:7680
	ds_read_b128 v[226:229], v184 offset:41024
	ds_read_b128 v[230:233], v184 offset:43584
	ds_read_b128 v[234:237], v184 offset:46144
	ds_read_b128 v[238:241], v184 offset:48704
	ds_read_b128 v[242:245], v185 offset:64
	ds_read_b128 v[246:249], v185 offset:2624
	s_waitcnt lgkmcnt(7)
	v_mfma_f32_16x16x32_bf16 v[94:97], v[202:205], v[210:213], v[94:97]
	v_mfma_f32_16x16x32_bf16 v[90:93], v[206:209], v[210:213], v[90:93]
	v_mfma_f32_16x16x32_bf16 v[86:89], v[214:217], v[210:213], v[86:89]
	v_mfma_f32_16x16x32_bf16 v[82:85], v[218:221], v[210:213], v[82:85]
	s_waitcnt lgkmcnt(6)
	v_mfma_f32_16x16x32_bf16 v[78:81], v[202:205], v[222:225], v[78:81]
	v_mfma_f32_16x16x32_bf16 v[74:77], v[206:209], v[222:225], v[74:77]
	v_mfma_f32_16x16x32_bf16 v[70:73], v[214:217], v[222:225], v[70:73]
	v_mfma_f32_16x16x32_bf16 v[66:69], v[218:221], v[222:225], v[66:69]
	s_waitcnt lgkmcnt(1)
	v_mfma_f32_16x16x32_bf16 v[126:129], v[226:229], v[242:245], v[126:129]
	v_mfma_f32_16x16x32_bf16 v[122:125], v[230:233], v[242:245], v[122:125]
	v_mfma_f32_16x16x32_bf16 v[118:121], v[234:237], v[242:245], v[118:121]
	v_mfma_f32_16x16x32_bf16 v[114:117], v[238:241], v[242:245], v[114:117]
	ds_read_b128 v[202:205], v185 offset:5184
	s_waitcnt lgkmcnt(1)
	v_mfma_f32_16x16x32_bf16 v[110:113], v[226:229], v[246:249], v[110:113]
	v_mfma_f32_16x16x32_bf16 v[106:109], v[230:233], v[246:249], v[106:109]
	v_mfma_f32_16x16x32_bf16 v[102:105], v[234:237], v[246:249], v[102:105]
	v_mfma_f32_16x16x32_bf16 v[98:101], v[238:241], v[246:249], v[98:101]
	ds_read_b128 v[206:209], v185 offset:7744
	s_waitcnt lgkmcnt(1)
	v_mfma_f32_16x16x32_bf16 v[94:97], v[226:229], v[202:205], v[94:97]
	v_mfma_f32_16x16x32_bf16 v[90:93], v[230:233], v[202:205], v[90:93]
	v_mfma_f32_16x16x32_bf16 v[86:89], v[234:237], v[202:205], v[86:89]
	v_mfma_f32_16x16x32_bf16 v[82:85], v[238:241], v[202:205], v[82:85]
	s_waitcnt lgkmcnt(0)
	v_mfma_f32_16x16x32_bf16 v[78:81], v[226:229], v[206:209], v[78:81]
	v_mfma_f32_16x16x32_bf16 v[74:77], v[230:233], v[206:209], v[74:77]
	v_mfma_f32_16x16x32_bf16 v[70:73], v[234:237], v[206:209], v[70:73]
	v_mfma_f32_16x16x32_bf16 v[66:69], v[238:241], v[206:209], v[66:69]
	s_setprio 0
	s_branch .LBB0_118
; template <bool VT>
; DI void gemm_mainloop(f32x4 (&acc)[8][4], const char* abase, const char* bbase, unsigned toff, u16* sA, u16* sB, int loff, int wm, int wn, int fr, int fq) {
;   const __amdgpu_buffer_rsrc_t ra_rs = __builtin_amdgcn_make_buffer_rsrc((void*)abase, (short)0, 256 * 2048, 0x00020000);
;   const __amdgpu_buffer_rsrc_t rb_rs = __builtin_amdgcn_make_buffer_rsrc((void*)bbase, (short)0, 128 * 2048, 0x00020000);
;   u32x4 ra[8], rb[4];
; #pragma unroll
;   for (int i = 0; i < 8; ++i) ra[i] = __builtin_amdgcn_raw_buffer_load_b128(ra_rs, (int)toff, i * 65536, 0);
; #pragma unroll
;   for (int i = 0; i < 4; ++i) rb[i] = __builtin_amdgcn_raw_buffer_load_b128(rb_rs, (int)toff, i * 65536, 0);
; template <int EPI>
; DI void gemm_tile(const Params& p, int layer, int mt, int nt, u16* sm, int wv) {
;     ...
; #pragma unroll
;   for (int i = 0; i < 8; ++i)
; #pragma unroll
;     for (int j = 0; j < 4; ++j)
; #pragma unroll
;       for (int e = 0; e < 4; ++e) acc[i][j][e] = 0.f;
.Lh1_pro:
	s_mov_b32 s87, s67
	s_mov_b32 s42, 0x20000
	s_mov_b32 s43, 0x30000
	s_mov_b32 s46, 0x60000
	s_mov_b32 s47, 0x70000
	s_mov_b32 s70, 0x0
	s_mov_b32 s71, 0x10000
	buffer_load_dwordx4 v[134:137], v0, s[64:67], s42 offen
	buffer_load_dwordx4 v[142:145], v0, s[64:67], s43 offen
	buffer_load_dwordx4 v[154:157], v0, s[64:67], s46 offen
	buffer_load_dwordx4 v[158:161], v0, s[64:67], s47 offen
	buffer_load_dwordx4 v[162:165], v0, s[84:87], s70 offen
	buffer_load_dwordx4 v[170:173], v0, s[84:87], s71 offen
	buffer_load_dwordx4 v[166:169], v0, s[84:87], s42 offen
	buffer_load_dwordx4 v[174:177], v0, s[84:87], s43 offen
	v_mov_b32_e32 v10, 0
	v_add_u32_e32 v184, v181, v182
	v_add_u32_e32 v185, v181, v183
	v_mov_b32_e32 v11, v10
	v_mov_b32_e32 v12, v10
	v_mov_b32_e32 v13, v10
	v_mov_b32_e32 v2, v10
	v_mov_b32_e32 v3, v10
	v_mov_b32_e32 v4, v10
	v_mov_b32_e32 v5, v10
	v_mov_b32_e32 v6, v10
	v_mov_b32_e32 v7, v10
	v_mov_b32_e32 v8, v10
	v_mov_b32_e32 v9, v10
	v_mov_b32_e32 v14, v10
	v_mov_b32_e32 v15, v10
	v_mov_b32_e32 v16, v10
	v_mov_b32_e32 v17, v10
	v_mov_b32_e32 v18, v10
	v_mov_b32_e32 v19, v10
	v_mov_b32_e32 v20, v10
	v_mov_b32_e32 v21, v10
	v_mov_b32_e32 v22, v10
	v_mov_b32_e32 v23, v10
	v_mov_b32_e32 v24, v10
	v_mov_b32_e32 v25, v10
	v_mov_b32_e32 v26, v10
	v_mov_b32_e32 v27, v10
	v_mov_b32_e32 v28, v10
	v_mov_b32_e32 v29, v10
	v_mov_b32_e32 v30, v10
	v_mov_b32_e32 v31, v10
	v_mov_b32_e32 v32, v10
	v_mov_b32_e32 v33, v10
	v_mov_b32_e32 v34, v10
	v_mov_b32_e32 v35, v10
	v_mov_b32_e32 v36, v10
	v_mov_b32_e32 v37, v10
	v_mov_b32_e32 v38, v10
	v_mov_b32_e32 v39, v10
	v_mov_b32_e32 v40, v10
	v_mov_b32_e32 v41, v10
	v_mov_b32_e32 v42, v10
	v_mov_b32_e32 v43, v10
	v_mov_b32_e32 v44, v10
	v_mov_b32_e32 v45, v10
	v_mov_b32_e32 v46, v10
	v_mov_b32_e32 v47, v10
	v_mov_b32_e32 v48, v10
	v_mov_b32_e32 v49, v10
	v_mov_b32_e32 v50, v10
	v_mov_b32_e32 v51, v10
	v_mov_b32_e32 v52, v10
	v_mov_b32_e32 v53, v10
	v_mov_b32_e32 v54, v10
	v_mov_b32_e32 v55, v10
	v_mov_b32_e32 v56, v10
	v_mov_b32_e32 v57, v10
	v_mov_b32_e32 v58, v10
	v_mov_b32_e32 v59, v10
	v_mov_b32_e32 v60, v10
	v_mov_b32_e32 v61, v10
	v_mov_b32_e32 v62, v10
	v_mov_b32_e32 v63, v10
	v_mov_b32_e32 v64, v10
	v_mov_b32_e32 v65, v10
	v_mov_b32_e32 v66, v10
	v_mov_b32_e32 v67, v10
	v_mov_b32_e32 v68, v10
	v_mov_b32_e32 v69, v10
	v_mov_b32_e32 v70, v10
	v_mov_b32_e32 v71, v10
	v_mov_b32_e32 v72, v10
	v_mov_b32_e32 v73, v10
	v_mov_b32_e32 v74, v10
	v_mov_b32_e32 v75, v10
	v_mov_b32_e32 v76, v10
	v_mov_b32_e32 v77, v10
	v_mov_b32_e32 v78, v10
	v_mov_b32_e32 v79, v10
	v_mov_b32_e32 v80, v10
	v_mov_b32_e32 v81, v10
	v_mov_b32_e32 v82, v10
	v_mov_b32_e32 v83, v10
	v_mov_b32_e32 v84, v10
	v_mov_b32_e32 v85, v10
	v_mov_b32_e32 v86, v10
	v_mov_b32_e32 v87, v10
	v_mov_b32_e32 v88, v10
	v_mov_b32_e32 v89, v10
	v_mov_b32_e32 v90, v10
	v_mov_b32_e32 v91, v10
	v_mov_b32_e32 v92, v10
	v_mov_b32_e32 v93, v10
	v_mov_b32_e32 v94, v10
	v_mov_b32_e32 v95, v10
	v_mov_b32_e32 v96, v10
	v_mov_b32_e32 v97, v10
	v_mov_b32_e32 v98, v10
	v_mov_b32_e32 v99, v10
	v_mov_b32_e32 v100, v10
	v_mov_b32_e32 v101, v10
	v_mov_b32_e32 v102, v10
	v_mov_b32_e32 v103, v10
	v_mov_b32_e32 v104, v10
	v_mov_b32_e32 v105, v10
	v_mov_b32_e32 v106, v10
	v_mov_b32_e32 v107, v10
	v_mov_b32_e32 v108, v10
	v_mov_b32_e32 v109, v10
	v_mov_b32_e32 v110, v10
	v_mov_b32_e32 v111, v10
	v_mov_b32_e32 v112, v10
	v_mov_b32_e32 v113, v10
	v_mov_b32_e32 v114, v10
	v_mov_b32_e32 v115, v10
	v_mov_b32_e32 v116, v10
	v_mov_b32_e32 v117, v10
	v_mov_b32_e32 v118, v10
	v_mov_b32_e32 v119, v10
	v_mov_b32_e32 v120, v10
	v_mov_b32_e32 v121, v10
	v_mov_b32_e32 v122, v10
	v_mov_b32_e32 v123, v10
	v_mov_b32_e32 v124, v10
	v_mov_b32_e32 v125, v10
	v_mov_b32_e32 v126, v10
	v_mov_b32_e32 v127, v10
	v_mov_b32_e32 v128, v10
	v_mov_b32_e32 v129, v10
	s_waitcnt vmcnt(8)
	buffer_load_dwordx4 v[130:133], v0, s[64:67], s42 offen offset:128
	buffer_load_dwordx4 v[138:141], v0, s[64:67], s43 offen offset:128
	buffer_load_dwordx4 v[146:149], v0, s[64:67], s46 offen offset:128
	buffer_load_dwordx4 v[150:153], v0, s[64:67], s47 offen offset:128
	buffer_load_dwordx4 v[66:69], v0, s[84:87], s70 offen offset:128
	buffer_load_dwordx4 v[70:73], v0, s[84:87], s71 offen offset:128
	buffer_load_dwordx4 v[74:77], v0, s[84:87], s42 offen offset:128
	buffer_load_dwordx4 v[78:81], v0, s[84:87], s43 offen offset:128
	s_mov_b32 s32, 7
; DI f32x4 mfma16(bf16x8 a, bf16x8 b, f32x4 c) { return __builtin_amdgcn_mfma_f32_16x16x32_bf16(a, b, c, 0, 0, 0); }
; template <bool VT>
; DI void gemm_kslab(f32x4 (&acc)[8][4], const u16* sA, const u16* sB, int wm, int wn, int fr, int fq) {
; #pragma unroll
;   for (int ks = 0; ks < 2; ++ks) {
;     bf16x8 tb[4], ta[8];
; #pragma unroll
;     for (int j = 0; j < 4; ++j) tb[j] = ldsv(sB + (wn * 64 + 16 * j + fr) * GSTR + ks * 32 + 8 * fq);
; #pragma unroll
;     for (int i = 0; i < 8; ++i) ta[i] = ldsv(sA + (wm * 128 + 16 * i + fr) * GSTR + ks * 32 + 8 * fq);
; #pragma unroll
;     for (int i = 0; i < 8; ++i)
; #pragma unroll
;       for (int j = 0; j < 4; ++j)
;         acc[i][j] = VT ? mfma16(ta[i], tb[j], acc[i][j]) : mfma16(tb[j], ta[i], acc[i][j]);
;   }
; template <bool VT>
; DI void gemm_mainloop(f32x4 (&acc)[8][4], const char* abase, const char* bbase, unsigned toff, u16* sA, u16* sB, int loff, int wm, int wn, int fr, int fq) {
;     ...
;   for (int kt = 0; kt < 16; ++kt) {
;     __syncthreads();
; #pragma unroll
;     for (int i = 0; i < 8; ++i) *(u32x4*)(sA + loff + i * 32 * GSTR) = ra[i];
; #pragma unroll
;     for (int i = 0; i < 4; ++i) *(u32x4*)(sB + loff + i * 32 * GSTR) = rb[i];
;     __syncthreads();
;     if (kt + 1 < 16) {
;       const int ko = (kt + 1) * 128;
; #pragma unroll
;       for (int i = 0; i < 8; ++i) ra[i] = __builtin_amdgcn_raw_buffer_load_b128(ra_rs, (int)toff, i * 65536 + ko, 0);
; #pragma unroll
;       for (int i = 0; i < 4; ++i) rb[i] = __builtin_amdgcn_raw_buffer_load_b128(rb_rs, (int)toff, i * 65536 + ko, 0);
;     }
;     __builtin_amdgcn_s_setprio(1);
;     gemm_kslab<VT>(acc, sA, sB, wm, wn, fr, fq);
;     __builtin_amdgcn_s_setprio(0);
.Lh1_loop:
	s_barrier
	s_waitcnt vmcnt(15)
	ds_write_b128 v180, v[134:137] offset:10240
	s_waitcnt vmcnt(14)
	ds_write_b128 v180, v[142:145] offset:15360
	s_waitcnt vmcnt(13)
	ds_write_b128 v180, v[154:157] offset:30720
	s_waitcnt vmcnt(12)
	ds_write_b128 v180, v[158:161] offset:35840
	s_waitcnt vmcnt(11)
	ds_write_b128 v180, v[162:165] offset:40960
	s_waitcnt vmcnt(10)
	ds_write_b128 v180, v[170:173] offset:46080
	s_waitcnt vmcnt(9)
	ds_write_b128 v180, v[166:169] offset:51200
	s_waitcnt vmcnt(8)
	ds_write_b128 v180, v[174:177] offset:56320
	s_waitcnt lgkmcnt(0)
	s_barrier
	s_addk_i32 s42, 0x100
	s_addk_i32 s43, 0x100
	s_addk_i32 s46, 0x100
	s_addk_i32 s47, 0x100
	s_addk_i32 s70, 0x100
	s_addk_i32 s71, 0x100
	buffer_load_dwordx4 v[134:137], v0, s[64:67], s42 offen
	buffer_load_dwordx4 v[142:145], v0, s[64:67], s43 offen
	buffer_load_dwordx4 v[154:157], v0, s[64:67], s46 offen
	buffer_load_dwordx4 v[158:161], v0, s[64:67], s47 offen
	buffer_load_dwordx4 v[162:165], v0, s[84:87], s70 offen
	buffer_load_dwordx4 v[170:173], v0, s[84:87], s71 offen
	buffer_load_dwordx4 v[166:169], v0, s[84:87], s42 offen
	buffer_load_dwordx4 v[174:177], v0, s[84:87], s43 offen
	s_setprio 1
	ds_read_b128 v[202:205], v184 offset:40960
	ds_read_b128 v[206:209], v184 offset:43520
	ds_read_b128 v[214:217], v184 offset:46080
	ds_read_b128 v[218:221], v184 offset:48640
	ds_read_b128 v[210:213], v185 offset:10240
	ds_read_b128 v[222:225], v185 offset:12800
	s_waitcnt lgkmcnt(1)
	v_mfma_f32_16x16x32_bf16 v[62:65], v[202:205], v[210:213], v[62:65]
	v_mfma_f32_16x16x32_bf16 v[58:61], v[206:209], v[210:213], v[58:61]
	v_mfma_f32_16x16x32_bf16 v[54:57], v[214:217], v[210:213], v[54:57]
	v_mfma_f32_16x16x32_bf16 v[50:53], v[218:221], v[210:213], v[50:53]
	ds_read_b128 v[210:213], v185 offset:15360
	s_waitcnt lgkmcnt(1)
	v_mfma_f32_16x16x32_bf16 v[46:49], v[202:205], v[222:225], v[46:49]
	v_mfma_f32_16x16x32_bf16 v[42:45], v[206:209], v[222:225], v[42:45]
	v_mfma_f32_16x16x32_bf16 v[38:41], v[214:217], v[222:225], v[38:41]
	v_mfma_f32_16x16x32_bf16 v[34:37], v[218:221], v[222:225], v[34:37]
	ds_read_b128 v[222:225], v185 offset:17920
	ds_read_b128 v[226:229], v184 offset:41024
	ds_read_b128 v[230:233], v184 offset:43584
	ds_read_b128 v[234:237], v184 offset:46144
	ds_read_b128 v[238:241], v184 offset:48704
	ds_read_b128 v[242:245], v185 offset:10304
	ds_read_b128 v[246:249], v185 offset:12864
	s_waitcnt lgkmcnt(7)
	v_mfma_f32_16x16x32_bf16 v[30:33], v[202:205], v[210:213], v[30:33]
	v_mfma_f32_16x16x32_bf16 v[26:29], v[206:209], v[210:213], v[26:29]
	v_mfma_f32_16x16x32_bf16 v[22:25], v[214:217], v[210:213], v[22:25]
	v_mfma_f32_16x16x32_bf16 v[18:21], v[218:221], v[210:213], v[18:21]
	s_waitcnt lgkmcnt(6)
	v_mfma_f32_16x16x32_bf16 v[14:17], v[202:205], v[222:225], v[14:17]
	v_mfma_f32_16x16x32_bf16 v[6:9], v[206:209], v[222:225], v[6:9]
	v_mfma_f32_16x16x32_bf16 v[2:5], v[214:217], v[222:225], v[2:5]
	v_mfma_f32_16x16x32_bf16 v[10:13], v[218:221], v[222:225], v[10:13]
	s_waitcnt lgkmcnt(1)
	v_mfma_f32_16x16x32_bf16 v[62:65], v[226:229], v[242:245], v[62:65]
	v_mfma_f32_16x16x32_bf16 v[58:61], v[230:233], v[242:245], v[58:61]
	v_mfma_f32_16x16x32_bf16 v[54:57], v[234:237], v[242:245], v[54:57]
	v_mfma_f32_16x16x32_bf16 v[50:53], v[238:241], v[242:245], v[50:53]
	ds_read_b128 v[202:205], v185 offset:15424
	s_waitcnt lgkmcnt(1)
	v_mfma_f32_16x16x32_bf16 v[46:49], v[226:229], v[246:249], v[46:49]
	v_mfma_f32_16x16x32_bf16 v[42:45], v[230:233], v[246:249], v[42:45]
	v_mfma_f32_16x16x32_bf16 v[38:41], v[234:237], v[246:249], v[38:41]
	v_mfma_f32_16x16x32_bf16 v[34:37], v[238:241], v[246:249], v[34:37]
	ds_read_b128 v[206:209], v185 offset:17984
	s_waitcnt lgkmcnt(1)
	v_mfma_f32_16x16x32_bf16 v[30:33], v[226:229], v[202:205], v[30:33]
	v_mfma_f32_16x16x32_bf16 v[26:29], v[230:233], v[202:205], v[26:29]
	v_mfma_f32_16x16x32_bf16 v[22:25], v[234:237], v[202:205], v[22:25]
	v_mfma_f32_16x16x32_bf16 v[18:21], v[238:241], v[202:205], v[18:21]
	s_waitcnt lgkmcnt(0)
	v_mfma_f32_16x16x32_bf16 v[14:17], v[226:229], v[206:209], v[14:17]
	v_mfma_f32_16x16x32_bf16 v[6:9], v[230:233], v[206:209], v[6:9]
	v_mfma_f32_16x16x32_bf16 v[2:5], v[234:237], v[206:209], v[2:5]
	v_mfma_f32_16x16x32_bf16 v[10:13], v[238:241], v[206:209], v[10:13]
	s_setprio 0
	s_barrier
	s_waitcnt vmcnt(15)
	ds_write_b128 v180, v[130:133] offset:10240
	s_waitcnt vmcnt(14)
	ds_write_b128 v180, v[138:141] offset:15360
	s_waitcnt vmcnt(13)
	ds_write_b128 v180, v[146:149] offset:30720
	s_waitcnt vmcnt(12)
	ds_write_b128 v180, v[150:153] offset:35840
	s_waitcnt vmcnt(11)
	ds_write_b128 v180, v[66:69] offset:40960
	s_waitcnt vmcnt(10)
	ds_write_b128 v180, v[70:73] offset:46080
	s_waitcnt vmcnt(9)
	ds_write_b128 v180, v[74:77] offset:51200
	s_waitcnt vmcnt(8)
	ds_write_b128 v180, v[78:81] offset:56320
	s_waitcnt lgkmcnt(0)
	s_barrier
; DI f32x4 mfma16(bf16x8 a, bf16x8 b, f32x4 c) { return __builtin_amdgcn_mfma_f32_16x16x32_bf16(a, b, c, 0, 0, 0); }
; template <bool VT>
; DI void gemm_kslab(f32x4 (&acc)[8][4], const u16* sA, const u16* sB, int wm, int wn, int fr, int fq) {
; #pragma unroll
;   for (int ks = 0; ks < 2; ++ks) {
;     bf16x8 tb[4], ta[8];
; #pragma unroll
;     for (int j = 0; j < 4; ++j) tb[j] = ldsv(sB + (wn * 64 + 16 * j + fr) * GSTR + ks * 32 + 8 * fq);
; #pragma unroll
;     for (int i = 0; i < 8; ++i) ta[i] = ldsv(sA + (wm * 128 + 16 * i + fr) * GSTR + ks * 32 + 8 * fq);
; #pragma unroll
;     for (int i = 0; i < 8; ++i)
; #pragma unroll
;       for (int j = 0; j < 4; ++j)
;         acc[i][j] = VT ? mfma16(ta[i], tb[j], acc[i][j]) : mfma16(tb[j], ta[i], acc[i][j]);
;   }
; template <bool VT>
; DI void gemm_mainloop(f32x4 (&acc)[8][4], const char* abase, const char* bbase, unsigned toff, u16* sA, u16* sB, int loff, int wm, int wn, int fr, int fq) {
;     ...
;   for (int kt = 0; kt < 16; ++kt) {
;     __syncthreads();
; #pragma unroll
;     for (int i = 0; i < 8; ++i) *(u32x4*)(sA + loff + i * 32 * GSTR) = ra[i];
; #pragma unroll
;     for (int i = 0; i < 4; ++i) *(u32x4*)(sB + loff + i * 32 * GSTR) = rb[i];
;     __syncthreads();
;     if (kt + 1 < 16) {
;       const int ko = (kt + 1) * 128;
; #pragma unroll
;       for (int i = 0; i < 8; ++i) ra[i] = __builtin_amdgcn_raw_buffer_load_b128(ra_rs, (int)toff, i * 65536 + ko, 0);
; #pragma unroll
;       for (int i = 0; i < 4; ++i) rb[i] = __builtin_amdgcn_raw_buffer_load_b128(rb_rs, (int)toff, i * 65536 + ko, 0);
;     }
;     __builtin_amdgcn_s_setprio(1);
;     gemm_kslab<VT>(acc, sA, sB, wm, wn, fr, fq);
;     __builtin_amdgcn_s_setprio(0);
	buffer_load_dwordx4 v[130:133], v0, s[64:67], s42 offen offset:128
	buffer_load_dwordx4 v[138:141], v0, s[64:67], s43 offen offset:128
	buffer_load_dwordx4 v[146:149], v0, s[64:67], s46 offen offset:128
	buffer_load_dwordx4 v[150:153], v0, s[64:67], s47 offen offset:128
	buffer_load_dwordx4 v[66:69], v0, s[84:87], s70 offen offset:128
	buffer_load_dwordx4 v[70:73], v0, s[84:87], s71 offen offset:128
	buffer_load_dwordx4 v[74:77], v0, s[84:87], s42 offen offset:128
	buffer_load_dwordx4 v[78:81], v0, s[84:87], s43 offen offset:128
	s_setprio 1
	ds_read_b128 v[202:205], v184 offset:40960
	ds_read_b128 v[206:209], v184 offset:43520
	ds_read_b128 v[214:217], v184 offset:46080
	ds_read_b128 v[218:221], v184 offset:48640
	ds_read_b128 v[210:213], v185 offset:10240
	ds_read_b128 v[222:225], v185 offset:12800
	s_waitcnt lgkmcnt(1)
	v_mfma_f32_16x16x32_bf16 v[62:65], v[202:205], v[210:213], v[62:65]
	v_mfma_f32_16x16x32_bf16 v[58:61], v[206:209], v[210:213], v[58:61]
	v_mfma_f32_16x16x32_bf16 v[54:57], v[214:217], v[210:213], v[54:57]
	v_mfma_f32_16x16x32_bf16 v[50:53], v[218:221], v[210:213], v[50:53]
	ds_read_b128 v[210:213], v185 offset:15360
	s_waitcnt lgkmcnt(1)
	v_mfma_f32_16x16x32_bf16 v[46:49], v[202:205], v[222:225], v[46:49]
	v_mfma_f32_16x16x32_bf16 v[42:45], v[206:209], v[222:225], v[42:45]
	v_mfma_f32_16x16x32_bf16 v[38:41], v[214:217], v[222:225], v[38:41]
	v_mfma_f32_16x16x32_bf16 v[34:37], v[218:221], v[222:225], v[34:37]
	ds_read_b128 v[222:225], v185 offset:17920
	ds_read_b128 v[226:229], v184 offset:41024
	ds_read_b128 v[230:233], v184 offset:43584
	ds_read_b128 v[234:237], v184 offset:46144
	ds_read_b128 v[238:241], v184 offset:48704
	ds_read_b128 v[242:245], v185 offset:10304
	ds_read_b128 v[246:249], v185 offset:12864
	s_waitcnt lgkmcnt(7)
	v_mfma_f32_16x16x32_bf16 v[30:33], v[202:205], v[210:213], v[30:33]
	v_mfma_f32_16x16x32_bf16 v[26:29], v[206:209], v[210:213], v[26:29]
	v_mfma_f32_16x16x32_bf16 v[22:25], v[214:217], v[210:213], v[22:25]
	v_mfma_f32_16x16x32_bf16 v[18:21], v[218:221], v[210:213], v[18:21]
	s_waitcnt lgkmcnt(6)
	v_mfma_f32_16x16x32_bf16 v[14:17], v[202:205], v[222:225], v[14:17]
	v_mfma_f32_16x16x32_bf16 v[6:9], v[206:209], v[222:225], v[6:9]
	v_mfma_f32_16x16x32_bf16 v[2:5], v[214:217], v[222:225], v[2:5]
	v_mfma_f32_16x16x32_bf16 v[10:13], v[218:221], v[222:225], v[10:13]
	s_waitcnt lgkmcnt(1)
	v_mfma_f32_16x16x32_bf16 v[62:65], v[226:229], v[242:245], v[62:65]
	v_mfma_f32_16x16x32_bf16 v[58:61], v[230:233], v[242:245], v[58:61]
	v_mfma_f32_16x16x32_bf16 v[54:57], v[234:237], v[242:245], v[54:57]
	v_mfma_f32_16x16x32_bf16 v[50:53], v[238:241], v[242:245], v[50:53]
	ds_read_b128 v[202:205], v185 offset:15424
	s_waitcnt lgkmcnt(1)
	v_mfma_f32_16x16x32_bf16 v[46:49], v[226:229], v[246:249], v[46:49]
	v_mfma_f32_16x16x32_bf16 v[42:45], v[230:233], v[246:249], v[42:45]
	v_mfma_f32_16x16x32_bf16 v[38:41], v[234:237], v[246:249], v[38:41]
	v_mfma_f32_16x16x32_bf16 v[34:37], v[238:241], v[246:249], v[34:37]
	ds_read_b128 v[206:209], v185 offset:17984
	s_waitcnt lgkmcnt(1)
	v_mfma_f32_16x16x32_bf16 v[30:33], v[226:229], v[202:205], v[30:33]
	v_mfma_f32_16x16x32_bf16 v[26:29], v[230:233], v[202:205], v[26:29]
	v_mfma_f32_16x16x32_bf16 v[22:25], v[234:237], v[202:205], v[22:25]
	v_mfma_f32_16x16x32_bf16 v[18:21], v[238:241], v[202:205], v[18:21]
	s_waitcnt lgkmcnt(0)
	v_mfma_f32_16x16x32_bf16 v[14:17], v[226:229], v[206:209], v[14:17]
	v_mfma_f32_16x16x32_bf16 v[6:9], v[230:233], v[206:209], v[6:9]
	v_mfma_f32_16x16x32_bf16 v[2:5], v[234:237], v[206:209], v[2:5]
	v_mfma_f32_16x16x32_bf16 v[10:13], v[238:241], v[206:209], v[10:13]
	s_setprio 0
	s_sub_i32 s32, s32, 1
	s_cmp_lg_u32 s32, 0
	s_cbranch_scc1 .Lh1_loop
	s_barrier
	s_waitcnt vmcnt(15)
	ds_write_b128 v180, v[134:137] offset:10240
	s_waitcnt vmcnt(14)
	ds_write_b128 v180, v[142:145] offset:15360
	s_waitcnt vmcnt(13)
	ds_write_b128 v180, v[154:157] offset:30720
	s_waitcnt vmcnt(12)
	ds_write_b128 v180, v[158:161] offset:35840
	s_waitcnt vmcnt(11)
	ds_write_b128 v180, v[162:165] offset:40960
	s_waitcnt vmcnt(10)
	ds_write_b128 v180, v[170:173] offset:46080
	s_waitcnt vmcnt(9)
	ds_write_b128 v180, v[166:169] offset:51200
	s_waitcnt vmcnt(8)
	ds_write_b128 v180, v[174:177] offset:56320
	s_waitcnt lgkmcnt(0)
	s_barrier
; DI f32x4 mfma16(bf16x8 a, bf16x8 b, f32x4 c) { return __builtin_amdgcn_mfma_f32_16x16x32_bf16(a, b, c, 0, 0, 0); }
; template <bool VT>
; DI void gemm_kslab(f32x4 (&acc)[8][4], const u16* sA, const u16* sB, int wm, int wn, int fr, int fq) {
; #pragma unroll
;   for (int ks = 0; ks < 2; ++ks) {
;     bf16x8 tb[4], ta[8];
; #pragma unroll
;     for (int j = 0; j < 4; ++j) tb[j] = ldsv(sB + (wn * 64 + 16 * j + fr) * GSTR + ks * 32 + 8 * fq);
; #pragma unroll
;     for (int i = 0; i < 8; ++i) ta[i] = ldsv(sA + (wm * 128 + 16 * i + fr) * GSTR + ks * 32 + 8 * fq);
; #pragma unroll
;     for (int i = 0; i < 8; ++i)
; #pragma unroll
;       for (int j = 0; j < 4; ++j)
;         acc[i][j] = VT ? mfma16(ta[i], tb[j], acc[i][j]) : mfma16(tb[j], ta[i], acc[i][j]);
;   }
; template <bool VT>
; DI void gemm_mainloop(f32x4 (&acc)[8][4], const char* abase, const char* bbase, unsigned toff, u16* sA, u16* sB, int loff, int wm, int wn, int fr, int fq) {
;     ...
;   for (int kt = 0; kt < 16; ++kt) {
;     __syncthreads();
; #pragma unroll
;     for (int i = 0; i < 8; ++i) *(u32x4*)(sA + loff + i * 32 * GSTR) = ra[i];
; #pragma unroll
;     for (int i = 0; i < 4; ++i) *(u32x4*)(sB + loff + i * 32 * GSTR) = rb[i];
;     __syncthreads();
;     if (kt + 1 < 16) {
;       const int ko = (kt + 1) * 128;
; #pragma unroll
;       for (int i = 0; i < 8; ++i) ra[i] = __builtin_amdgcn_raw_buffer_load_b128(ra_rs, (int)toff, i * 65536 + ko, 0);
; #pragma unroll
;       for (int i = 0; i < 4; ++i) rb[i] = __builtin_amdgcn_raw_buffer_load_b128(rb_rs, (int)toff, i * 65536 + ko, 0);
;     }
;     __builtin_amdgcn_s_setprio(1);
;     gemm_kslab<VT>(acc, sA, sB, wm, wn, fr, fq);
;     __builtin_amdgcn_s_setprio(0);
	s_setprio 1
	ds_read_b128 v[202:205], v184 offset:40960
	ds_read_b128 v[206:209], v184 offset:43520
	ds_read_b128 v[214:217], v184 offset:46080
	ds_read_b128 v[218:221], v184 offset:48640
	ds_read_b128 v[210:213], v185 offset:10240
	ds_read_b128 v[222:225], v185 offset:12800
	s_waitcnt lgkmcnt(1)
	v_mfma_f32_16x16x32_bf16 v[62:65], v[202:205], v[210:213], v[62:65]
	v_mfma_f32_16x16x32_bf16 v[58:61], v[206:209], v[210:213], v[58:61]
	v_mfma_f32_16x16x32_bf16 v[54:57], v[214:217], v[210:213], v[54:57]
	v_mfma_f32_16x16x32_bf16 v[50:53], v[218:221], v[210:213], v[50:53]
	ds_read_b128 v[210:213], v185 offset:15360
	s_waitcnt lgkmcnt(1)
	v_mfma_f32_16x16x32_bf16 v[46:49], v[202:205], v[222:225], v[46:49]
	v_mfma_f32_16x16x32_bf16 v[42:45], v[206:209], v[222:225], v[42:45]
	v_mfma_f32_16x16x32_bf16 v[38:41], v[214:217], v[222:225], v[38:41]
	v_mfma_f32_16x16x32_bf16 v[34:37], v[218:221], v[222:225], v[34:37]
	ds_read_b128 v[222:225], v185 offset:17920
	ds_read_b128 v[226:229], v184 offset:41024
	ds_read_b128 v[230:233], v184 offset:43584
	ds_read_b128 v[234:237], v184 offset:46144
	ds_read_b128 v[238:241], v184 offset:48704
	ds_read_b128 v[242:245], v185 offset:10304
	ds_read_b128 v[246:249], v185 offset:12864
	s_waitcnt lgkmcnt(7)
	v_mfma_f32_16x16x32_bf16 v[30:33], v[202:205], v[210:213], v[30:33]
	v_mfma_f32_16x16x32_bf16 v[26:29], v[206:209], v[210:213], v[26:29]
	v_mfma_f32_16x16x32_bf16 v[22:25], v[214:217], v[210:213], v[22:25]
	v_mfma_f32_16x16x32_bf16 v[18:21], v[218:221], v[210:213], v[18:21]
	s_waitcnt lgkmcnt(6)
	v_mfma_f32_16x16x32_bf16 v[14:17], v[202:205], v[222:225], v[14:17]
	v_mfma_f32_16x16x32_bf16 v[6:9], v[206:209], v[222:225], v[6:9]
	v_mfma_f32_16x16x32_bf16 v[2:5], v[214:217], v[222:225], v[2:5]
	v_mfma_f32_16x16x32_bf16 v[10:13], v[218:221], v[222:225], v[10:13]
	s_waitcnt lgkmcnt(1)
	v_mfma_f32_16x16x32_bf16 v[62:65], v[226:229], v[242:245], v[62:65]
	v_mfma_f32_16x16x32_bf16 v[58:61], v[230:233], v[242:245], v[58:61]
	v_mfma_f32_16x16x32_bf16 v[54:57], v[234:237], v[242:245], v[54:57]
	v_mfma_f32_16x16x32_bf16 v[50:53], v[238:241], v[242:245], v[50:53]
	ds_read_b128 v[202:205], v185 offset:15424
	s_waitcnt lgkmcnt(1)
	v_mfma_f32_16x16x32_bf16 v[46:49], v[226:229], v[246:249], v[46:49]
	v_mfma_f32_16x16x32_bf16 v[42:45], v[230:233], v[246:249], v[42:45]
	v_mfma_f32_16x16x32_bf16 v[38:41], v[234:237], v[246:249], v[38:41]
	v_mfma_f32_16x16x32_bf16 v[34:37], v[238:241], v[246:249], v[34:37]
	ds_read_b128 v[206:209], v185 offset:17984
	s_waitcnt lgkmcnt(1)
	v_mfma_f32_16x16x32_bf16 v[30:33], v[226:229], v[202:205], v[30:33]
	v_mfma_f32_16x16x32_bf16 v[26:29], v[230:233], v[202:205], v[26:29]
	v_mfma_f32_16x16x32_bf16 v[22:25], v[234:237], v[202:205], v[22:25]
	v_mfma_f32_16x16x32_bf16 v[18:21], v[238:241], v[202:205], v[18:21]
	s_waitcnt lgkmcnt(0)
	v_mfma_f32_16x16x32_bf16 v[14:17], v[226:229], v[206:209], v[14:17]
	v_mfma_f32_16x16x32_bf16 v[6:9], v[230:233], v[206:209], v[6:9]
	v_mfma_f32_16x16x32_bf16 v[2:5], v[234:237], v[206:209], v[2:5]
	v_mfma_f32_16x16x32_bf16 v[10:13], v[238:241], v[206:209], v[10:13]
	s_setprio 0
	s_barrier
	s_waitcnt vmcnt(7)
	ds_write_b128 v180, v[130:133] offset:10240
	s_waitcnt vmcnt(6)
	ds_write_b128 v180, v[138:141] offset:15360
	s_waitcnt vmcnt(5)
	ds_write_b128 v180, v[146:149] offset:30720
	s_waitcnt vmcnt(4)
	ds_write_b128 v180, v[150:153] offset:35840
	s_waitcnt vmcnt(3)
	ds_write_b128 v180, v[66:69] offset:40960
	s_waitcnt vmcnt(2)
	ds_write_b128 v180, v[70:73] offset:46080
	s_waitcnt vmcnt(1)
	ds_write_b128 v180, v[74:77] offset:51200
	s_waitcnt vmcnt(0)
	ds_write_b128 v180, v[78:81] offset:56320
	s_waitcnt lgkmcnt(0)
	s_barrier
	s_setprio 1
	ds_read_b128 v[202:205], v184 offset:40960
	ds_read_b128 v[206:209], v184 offset:43520
	ds_read_b128 v[214:217], v184 offset:46080
	ds_read_b128 v[218:221], v184 offset:48640
	ds_read_b128 v[210:213], v185 offset:10240
	ds_read_b128 v[222:225], v185 offset:12800
	s_waitcnt lgkmcnt(1)
	v_mfma_f32_16x16x32_bf16 v[62:65], v[202:205], v[210:213], v[62:65]
	v_mfma_f32_16x16x32_bf16 v[58:61], v[206:209], v[210:213], v[58:61]
	v_mfma_f32_16x16x32_bf16 v[54:57], v[214:217], v[210:213], v[54:57]
	v_mfma_f32_16x16x32_bf16 v[50:53], v[218:221], v[210:213], v[50:53]
	ds_read_b128 v[210:213], v185 offset:15360
	s_waitcnt lgkmcnt(1)
	v_mfma_f32_16x16x32_bf16 v[46:49], v[202:205], v[222:225], v[46:49]
	v_mfma_f32_16x16x32_bf16 v[42:45], v[206:209], v[222:225], v[42:45]
	v_mfma_f32_16x16x32_bf16 v[38:41], v[214:217], v[222:225], v[38:41]
	v_mfma_f32_16x16x32_bf16 v[34:37], v[218:221], v[222:225], v[34:37]
	ds_read_b128 v[222:225], v185 offset:17920
	ds_read_b128 v[226:229], v184 offset:41024
	ds_read_b128 v[230:233], v184 offset:43584
	ds_read_b128 v[234:237], v184 offset:46144
	ds_read_b128 v[238:241], v184 offset:48704
	ds_read_b128 v[242:245], v185 offset:10304
	ds_read_b128 v[246:249], v185 offset:12864
	s_waitcnt lgkmcnt(7)
	v_mfma_f32_16x16x32_bf16 v[30:33], v[202:205], v[210:213], v[30:33]
	v_mfma_f32_16x16x32_bf16 v[26:29], v[206:209], v[210:213], v[26:29]
	v_mfma_f32_16x16x32_bf16 v[22:25], v[214:217], v[210:213], v[22:25]
	v_mfma_f32_16x16x32_bf16 v[18:21], v[218:221], v[210:213], v[18:21]
	s_waitcnt lgkmcnt(6)
	v_mfma_f32_16x16x32_bf16 v[14:17], v[202:205], v[222:225], v[14:17]
	v_mfma_f32_16x16x32_bf16 v[6:9], v[206:209], v[222:225], v[6:9]
	v_mfma_f32_16x16x32_bf16 v[2:5], v[214:217], v[222:225], v[2:5]
	v_mfma_f32_16x16x32_bf16 v[10:13], v[218:221], v[222:225], v[10:13]
	s_waitcnt lgkmcnt(1)
	v_mfma_f32_16x16x32_bf16 v[62:65], v[226:229], v[242:245], v[62:65]
	v_mfma_f32_16x16x32_bf16 v[58:61], v[230:233], v[242:245], v[58:61]
	v_mfma_f32_16x16x32_bf16 v[54:57], v[234:237], v[242:245], v[54:57]
	v_mfma_f32_16x16x32_bf16 v[50:53], v[238:241], v[242:245], v[50:53]
	ds_read_b128 v[202:205], v185 offset:15424
	s_waitcnt lgkmcnt(1)
	v_mfma_f32_16x16x32_bf16 v[46:49], v[226:229], v[246:249], v[46:49]
	v_mfma_f32_16x16x32_bf16 v[42:45], v[230:233], v[246:249], v[42:45]
	v_mfma_f32_16x16x32_bf16 v[38:41], v[234:237], v[246:249], v[38:41]
	v_mfma_f32_16x16x32_bf16 v[34:37], v[238:241], v[246:249], v[34:37]
	ds_read_b128 v[206:209], v185 offset:17984
	s_waitcnt lgkmcnt(1)
	v_mfma_f32_16x16x32_bf16 v[30:33], v[226:229], v[202:205], v[30:33]
	v_mfma_f32_16x16x32_bf16 v[26:29], v[230:233], v[202:205], v[26:29]
	v_mfma_f32_16x16x32_bf16 v[22:25], v[234:237], v[202:205], v[22:25]
	v_mfma_f32_16x16x32_bf16 v[18:21], v[238:241], v[202:205], v[18:21]
	s_waitcnt lgkmcnt(0)
	v_mfma_f32_16x16x32_bf16 v[14:17], v[226:229], v[206:209], v[14:17]
	v_mfma_f32_16x16x32_bf16 v[6:9], v[230:233], v[206:209], v[6:9]
	v_mfma_f32_16x16x32_bf16 v[2:5], v[234:237], v[206:209], v[2:5]
	v_mfma_f32_16x16x32_bf16 v[10:13], v[238:241], v[206:209], v[10:13]
	s_setprio 0
	s_branch .LBB0_118

; DI void attn_item_A(const Params& p, int layer, int b, int head, int qb, u16* sm, float lam, float lam_init, int wv) {
;     ...
;   const int t7 = tid & 127, wp = t7 >> 6;
;   const int csrc = (lane & 7) ^ ((4 * wp + (lane >> 4)) & 7);
;   const int row0 = wp * 8 + (lane >> 3);
;   const u16* kg = projb + koff + csrc * 8;
;   const u16* vg = p.vt + ((size_t)(b * NVH + vh) * 64) * SEQ + csrc * 8;
;   float zf = 0.f;
;   asm volatile("" : "+v"(zf));
;   f32x16 o[2][2];
; #pragma unroll
;   for (int a = 0; a < 2; ++a)
; #pragma unroll
;     for (int d = 0; d < 2; ++d)
; #pragma unroll
;       for (int e = 0; e < 16; ++e) o[a][d][e] = zf;
;   float m0 = 0.f, m1 = 0.f;
;   f32x4 ls0 = {zf, zf, zf, zf}, ls1 = {zf, zf, zf, zf};
;   const bf16x8 ones = rowsum_ones(lane);
;   bool started = false;
;   const int npairs = (qb >> 1) + 1;
;   const int T0 = 2 * (npairs - 1) + kh;
;   const bool v0 = (T0 <= qb);
;   auto dma_tile = [&](int T, int c) {
;     const int k0 = 64 * T;
;     u16* Kd = Kb0 + c * (2 * 64 * 64) + wp * (8 * 64);
; #pragma unroll
;     for (int i = 0; i < 4; ++i) {
;       __builtin_amdgcn_global_load_lds((const unsigned*)(kg + (size_t)(k0 + row0 + 16 * i) * DIN), (unsigned*)(Kd + i * 16 * 64), 16, 0, 0);
;       __builtin_amdgcn_global_load_lds((const unsigned*)(vg + (size_t)(row0 + 16 * i) * SEQ + k0), (unsigned*)(Kd + 64 * 64 + i * 16 * 64), 16, 0, 0);
;     }
;   };
.LBB0_276:
	s_or_b64 exec, exec, s[18:19]
	s_waitcnt vmcnt(0)
	v_and_b32_e32 v205, 60, v125
	s_waitcnt vmcnt(0) lgkmcnt(0)
	s_barrier
	s_and_saveexec_b64 s[18:19], vcc
	s_cbranch_execz .LBB0_292
	v_add_u32_e32 v66, v120, v171
	v_sub_u32_e32 v66, v66, v124
	v_lshlrev_b32_e32 v67, 6, v118
	v_sub_u32_e32 v66, v66, v67
	v_lshlrev_b32_e32 v206, 6, v173
	v_lshlrev_b32_e32 v67, 6, v119
	v_sub_u32_e32 v66, v66, v206
	v_and_b32_e32 v67, 0xffffff80, v67
	v_sub_u32_e32 v66, v66, v67
	v_add_u32_e32 v207, 0x2040, v66
	v_add_u32_e32 v66, v118, v173
	s_movk_i32 s2, 0xff7f
	v_add3_u32 v208, v66, v123, s2
	v_or_b32_e32 v66, v121, v67
	v_cmp_gt_u32_e64 s[36:37], 16, v171
	v_add_u32_e32 v209, v66, v122
	v_add_u32_e32 v210, 0xffffff00, v67
	v_add_u32_e32 v72, v206, v209
	v_add_u32_e32 v68, 0xffffff00, v72
	v_mad_i64_i32 v[68:69], s[38:39], v68, s8, v[160:161]
	v_readlane_b32 s22, v250, 19
	v_add_u32_e32 v66, v206, v210
	v_ashrrev_i32_e32 v67, 31, v66
	v_lshl_add_u64 v[68:69], v[68:69], 0, s[68:69]
	v_lshlrev_b64 v[66:67], 1, v[66:67]
	v_or_b32_e32 v74, v121, v122
	v_subrev_u32_e32 v75, s22, v160
	v_lshl_add_u64 v[70:71], v[162:163], 0, v[66:67]
	v_mul_u32_u24_e32 v76, 0x1a00, v74
	v_lshlrev_b32_e32 v77, 14, v74
	v_add_u32_e32 v76, v76, v75
	v_add_u32_e32 v77, v77, v75
	v_sub_co_u32_e32 v68, vcc, v68, v76
	s_nop 1
	v_subbrev_co_u32_e32 v69, vcc, 0, v69, vcc
	v_sub_co_u32_e32 v70, vcc, v70, v77
	s_nop 1
	v_subbrev_co_u32_e32 v71, vcc, 0, v71, vcc
	v_mov_b32_e32 v160, v76
	v_readfirstlane_b32 s98, v68
	v_readfirstlane_b32 s99, v69
	v_readfirstlane_b32 s100, v70
	v_readfirstlane_b32 s101, v71
	v_readfirstlane_b32 s87, v177
	v_add_u32_e32 v161, 0x1a000, v76
	v_add_u32_e32 v162, 0x34000, v76
	v_add_u32_e32 v163, 0x4e000, v76
	v_mov_b32_e32 v164, v77
	v_add_u32_e32 v165, 0x40000, v77
	v_add_u32_e32 v166, 0x80000, v77
	v_add_u32_e32 v167, 0xc0000, v77
	s_movk_i32 s64, 0x2000
	s_mov_b32 s65, 0
	s_mov_b64 s[40:41], 0
	s_mov_b64 s[42:43], s[4:5]
	s_branch .LBB0_279
	s_nop 0
	s_nop 0
	s_nop 0
